# v2c + one static s_setprio 1 for the younger wave half (waves 4-7) during the attention and S5 phases
# speedup vs baseline: 1.0081x; 1.0018x over previous
.LBB0_339:
	v_readlane_b32 s0, v255, 3
	v_readlane_b32 s1, v255, 4
	s_cmp_lt_i32 s0, 5
	s_cselect_b64 s[0:1], -1, 0
	s_and_b64 s[10:11], s[0:1], s[4:5]
	s_andn2_b64 vcc, exec, s[10:11]
	s_cbranch_vccnz .LBB0_355
	v_readfirstlane_b32 s100, v0
	s_nop 3
	s_bitcmp1_b32 s100, 8
	s_cbranch_scc0 .Lprio_s5
	s_setprio 1
.Lprio_s5:
	v_mov_b32_e32 v2, v0
	v_readlane_b32 s0, v255, 11
	s_add_u32 s42, s70, 0x300000
	v_lshrrev_b32_e32 v5, 3, v2
	v_and_b32_e32 v6, 5, v2
	s_mulk_i32 s0, 0x2200
	v_and_or_b32 v5, v5, 2, v6
	v_lshrrev_b32_e32 v7, 2, v2
	s_addc_u32 s43, s71, 0
	s_add_i32 s0, s0, 0
	v_lshlrev_b32_e32 v5, 2, v5
	v_bfe_u32 v6, v2, 1, 1
	v_and_b32_e32 v8, 2, v7
	v_and_b32_e32 v3, 63, v2
	v_and_b32_e32 v1, 31, v2
	v_bfe_u32 v4, v2, 5, 1
	v_or3_b32 v126, v5, v6, v8
	v_lshlrev_b32_e32 v5, 6, v2
	v_mov_b32_e32 v131, 0
	s_movk_i32 s1, 0x440
	v_mov_b32_e32 v2, s0
	s_movk_i32 s0, 0x110
	v_lshlrev_b32_e32 v128, 2, v4
	v_mad_u32_u24 v6, v4, s1, v2
	v_mad_u32_u24 v8, v1, s0, v2
	v_lshlrev_b32_e32 v2, 4, v4
	v_cmp_gt_u32_e64 s[6:7], 32, v3
	s_movk_i32 s0, 0x3c0
	v_mov_b32_e32 v3, v131
	v_and_or_b32 v9, v5, s0, v128
	v_lshl_add_u64 v[4:5], s[70:71], 0, v[2:3]
	s_mov_b64 s[0:1], 0x308000
	v_readlane_b32 s2, v255, 13
	v_lshl_add_u64 v[134:135], v[4:5], 0, s[0:1]
	v_and_b32_e32 v4, 8, v7
	v_mov_b32_e32 v5, v131
	s_cmpk_lt_i32 s2, 0x800
	v_lshlrev_b32_e32 v130, 2, v1
	v_lshl_add_u64 v[4:5], s[70:71], 0, v[4:5]
	s_mov_b64 s[0:1], 0x15c00000
	s_mov_b32 s45, 0
	v_cmp_gt_u32_e64 s[4:5], 16, v1
	v_lshl_add_u64 v[132:133], s[68:69], 0, v[130:131]
	v_lshl_add_u64 v[136:137], v[4:5], 0, s[0:1]
	s_mov_b64 s[52:53], 0
	s_mov_b64 s[54:55], -1
	s_cselect_b64 s[50:51], -1, 0
	s_mov_b32 s14, 0x10800000
	s_movk_i32 s15, 0x7fff
	s_mov_b64 s[56:57], 0x10000
	v_lshlrev_b32_e32 v127, 2, v9
	s_mov_b32 s34, 0x7060302
	s_mov_b32 s35, 0x5040100
	v_add_u32_e32 v129, v6, v130
	v_add_u32_e32 v206, v8, v2
	v_readlane_b32 s3, v255, 14
	s_branch .LBB0_342

.LBB0_355:
	s_setprio 0
	v_readlane_b32 s0, v255, 3
	v_readlane_b32 s1, v255, 4
	s_cmp_gt_i32 s1, 5
	s_cselect_b64 s[4:5], -1, 0
	s_and_b64 s[0:1], s[10:11], s[4:5]
	s_andn2_b64 vcc, exec, s[0:1]
	s_cbranch_vccnz .LBB0_409
	s_waitcnt vmcnt(0)
	s_waitcnt lgkmcnt(0)
	s_barrier
	s_mov_b64 s[6:7], exec
	v_readlane_b32 s0, v255, 9
	v_readlane_b32 s1, v255, 10
	s_and_b64 s[0:1], s[6:7], s[0:1]
	s_mov_b64 exec, s[0:1]
	s_cbranch_execz .LBB0_408
	s_add_i32 s0, 0, 0x21160
	v_mov_b32_e32 v1, s0
	s_waitcnt vmcnt(0) expcnt(0) lgkmcnt(0)
	ds_read_b32 v3, v1
	s_add_i32 s0, 0, 0x21164
	v_mov_b32_e32 v1, s0
	ds_read_b32 v1, v1
	s_waitcnt lgkmcnt(1)
	v_cmp_ne_u32_e32 vcc, 0, v3
	s_cbranch_vccnz .LBB0_372
	v_readlane_b32 s0, v255, 0
	v_readlane_b32 s1, v255, 1
	s_load_dwordx2 s[10:11], s[0:1], 0x4
	s_add_u32 s0, s70, 0x4200
	s_addc_u32 s1, s71, 0
	s_add_u32 s8, s70, 0x4400
	s_addc_u32 s9, s71, 0
	s_waitcnt lgkmcnt(0)
	s_mul_i32 s40, s10, s72
	s_add_u32 s10, s70, 0x4500
	s_mul_i32 s40, s40, s11
	s_addc_u32 s11, s71, 0
	s_add_u32 s24, s70, 0x4600
	s_addc_u32 s25, s71, 0
	s_add_u32 s26, s70, 0x4700
	s_addc_u32 s27, s71, 0
	s_add_u32 s34, s70, 0x4800
	s_addc_u32 s35, s71, 0
	s_add_u32 s36, s70, 0x4900
	s_addc_u32 s37, s71, 0
	s_add_u32 s38, s70, 0x4a00
	s_addc_u32 s39, s71, 0
	s_add_u32 s42, s70, 0x4b00
	s_addc_u32 s43, s71, 0
	s_add_u32 s44, s70, 0x4c00
	s_addc_u32 s45, s71, 0
	s_add_u32 s50, s70, 0x4d00
	s_addc_u32 s51, s71, 0
	s_add_u32 s52, s70, 0x4e00
	s_addc_u32 s53, s71, 0
	s_add_u32 s54, s70, 0x4f00
	s_addc_u32 s55, s71, 0
	s_add_u32 s56, s70, 0x5000
	s_addc_u32 s57, s71, 0
	s_add_u32 s58, s70, 0x5100
	s_addc_u32 s59, s71, 0
	s_add_u32 s60, s70, 0x5200
	s_addc_u32 s61, s71, 0
	s_add_u32 s62, s70, 0x5300
	s_addc_u32 s63, s71, 0
	s_mov_b32 s41, 1
	v_mov_b32_e32 v17, 0
	s_branch .LBB0_360

.LBB0_1054:
	v_readlane_b32 s0, v255, 3
	v_readlane_b32 s1, v255, 4
	s_cmp_lt_i32 s0, 16
	s_cselect_b64 s[0:1], -1, 0
	s_add_u32 s6, s70, 0x1e000000
	s_addc_u32 s7, s71, 0
	s_and_b64 s[8:9], s[0:1], s[2:3]
	s_andn2_b64 vcc, exec, s[8:9]
	v_mbcnt_lo_u32_b32 v1, -1, 0
	s_cbranch_vccnz .LBB0_1193
	v_readfirstlane_b32 s100, v0
	s_nop 3
	s_bitcmp1_b32 s100, 8
	s_cbranch_scc0 .Lprio_attn
	s_setprio 1
.Lprio_attn:
	v_and_b32_e32 v2, 63, v0
	v_lshlrev_b32_e32 v2, 2, v2
	global_load_dword v3, v2, s[46:47]
	global_load_dword v4, v2, s[46:47] offset:256
	global_load_dword v5, v2, s[46:47] offset:512
	global_load_dword v6, v2, s[46:47] offset:768
	v_mbcnt_hi_u32_b32 v2, -1, v1
	v_and_b32_e32 v7, 64, v2
	v_xor_b32_e32 v8, 1, v2
	v_add_u32_e32 v7, 64, v7
	v_cmp_lt_i32_e32 vcc, v8, v7
	v_xor_b32_e32 v9, 2, v2
	v_xor_b32_e32 v10, 4, v2
	v_cndmask_b32_e32 v8, v2, v8, vcc
	v_lshlrev_b32_e32 v8, 2, v8
	v_cmp_lt_i32_e32 vcc, v9, v7
	v_xor_b32_e32 v11, 8, v2
	v_xor_b32_e32 v12, 16, v2
	v_cndmask_b32_e32 v9, v2, v9, vcc
	v_lshlrev_b32_e32 v9, 2, v9
	v_cmp_lt_i32_e32 vcc, v10, v7
	v_xor_b32_e32 v13, 32, v2
	s_mov_b32 s1, 0x3fb8aa3b
	s_mov_b32 s2, 0xc2ce8ed0
	v_readfirstlane_b32 s0, v0
	s_mov_b32 s11, 0
	s_waitcnt vmcnt(2)
	v_mul_f32_e32 v14, v3, v4
	ds_bpermute_b32 v14, v8, v14
	s_waitcnt vmcnt(0)
	v_mul_f32_e32 v15, v5, v6
	ds_bpermute_b32 v8, v8, v15
	s_waitcnt lgkmcnt(1)
	v_fmac_f32_e32 v14, v3, v4
	ds_bpermute_b32 v3, v9, v14
	s_waitcnt lgkmcnt(1)
	v_fmac_f32_e32 v8, v5, v6
	ds_bpermute_b32 v4, v9, v8
	v_cndmask_b32_e32 v5, v2, v10, vcc
	v_lshlrev_b32_e32 v5, 2, v5
	s_waitcnt lgkmcnt(1)
	v_add_f32_e32 v3, v14, v3
	ds_bpermute_b32 v6, v5, v3
	s_waitcnt lgkmcnt(1)
	v_add_f32_e32 v4, v8, v4
	ds_bpermute_b32 v5, v5, v4
	v_cmp_lt_i32_e32 vcc, v11, v7
	s_waitcnt lgkmcnt(1)
	v_add_f32_e32 v3, v3, v6
	v_cndmask_b32_e32 v8, v2, v11, vcc
	v_lshlrev_b32_e32 v8, 2, v8
	s_waitcnt lgkmcnt(0)
	v_add_f32_e32 v4, v4, v5
	ds_bpermute_b32 v5, v8, v3
	ds_bpermute_b32 v6, v8, v4
	v_cmp_lt_i32_e32 vcc, v12, v7
	s_waitcnt lgkmcnt(1)
	v_add_f32_e32 v3, v3, v5
	v_cndmask_b32_e32 v8, v2, v12, vcc
	v_lshlrev_b32_e32 v8, 2, v8
	s_waitcnt lgkmcnt(0)
	v_add_f32_e32 v4, v4, v6
	ds_bpermute_b32 v5, v8, v3
	ds_bpermute_b32 v6, v8, v4
	v_cmp_lt_i32_e32 vcc, v13, v7
	s_waitcnt lgkmcnt(1)
	v_add_f32_e32 v3, v3, v5
	v_cndmask_b32_e32 v2, v2, v13, vcc
	v_lshlrev_b32_e32 v2, 2, v2
	s_waitcnt lgkmcnt(0)
	v_add_f32_e32 v4, v4, v6
	ds_bpermute_b32 v5, v2, v3
	ds_bpermute_b32 v2, v2, v4
	s_waitcnt lgkmcnt(1)
	v_add_f32_e32 v3, v3, v5
	s_waitcnt lgkmcnt(0)
	v_add_f32_e32 v2, v4, v2
	v_mul_f32_e32 v4, 0x3fb8aa3b, v3
	v_mul_f32_e32 v5, 0x3fb8aa3b, v2
	v_fma_f32 v6, v3, s1, -v4
	v_rndne_f32_e32 v7, v4
	v_fma_f32 v8, v2, s1, -v5
	v_rndne_f32_e32 v9, v5
	v_fmac_f32_e32 v6, 0x32a5705f, v3
	v_sub_f32_e32 v4, v4, v7
	v_fmac_f32_e32 v8, 0x32a5705f, v2
	v_sub_f32_e32 v5, v5, v9
	v_add_f32_e32 v4, v4, v6
	v_cvt_i32_f32_e32 v7, v7
	v_add_f32_e32 v5, v5, v8
	v_exp_f32_e32 v4, v4
	v_cvt_i32_f32_e32 v9, v9
	v_exp_f32_e32 v5, v5
	v_cmp_ngt_f32_e32 vcc, s2, v3
	v_ldexp_f32 v4, v4, v7
	s_mov_b32 s1, 0x42b17218
	v_ldexp_f32 v5, v5, v9
	v_cndmask_b32_e32 v4, 0, v4, vcc
	v_cmp_ngt_f32_e32 vcc, s2, v2
	v_mov_b32_e32 v6, 0x7f800000
	s_nop 0
	v_cndmask_b32_e32 v5, 0, v5, vcc
	v_cmp_nlt_f32_e32 vcc, s1, v3
	s_nop 1
	v_cndmask_b32_e32 v3, v6, v4, vcc
	v_cmp_nlt_f32_e32 vcc, s1, v2
	v_readlane_b32 s1, v255, 2
	s_cmpk_gt_i32 s1, 0xff
	v_cndmask_b32_e32 v2, v6, v5, vcc
	v_sub_f32_e32 v2, v3, v2
	s_nop 0
	v_readfirstlane_b32 s1, v2
	s_cbranch_scc1 .LBB0_1193
	v_mov_b32_e32 v2, 0x3eb60549
	v_add_f32_e32 v230, s1, v2
	s_ashr_i32 s1, s72, 31
	s_lshr_b32 s1, s1, 27
	s_add_i32 s1, s72, s1
	v_readlane_b32 s4, v255, 2
	s_ashr_i32 s40, s1, 5
	s_ashr_i32 s1, s4, 31
	s_lshr_b32 s1, s1, 27
	s_add_i32 s1, s4, s1
	s_lshr_b32 s2, s0, 6
	s_ashr_i32 s41, s1, 5
	s_andn2_b32 s1, s1, 31
	s_bfe_u32 s50, s2, 0x10001
	s_lshl_b32 s2, s0, 9
	s_sub_i32 s42, s4, s1
	s_and_b32 s2, s2, 0x8000
	s_bfe_u32 s3, s0, 0x20006
	s_ashr_i32 s43, s42, 1
	s_lshr_b32 s1, s0, 2
	s_or_b32 s51, s2, 0x4000000
	s_lshl_b32 s2, s42, 8
	s_and_b32 s44, s42, 1
	s_sub_i32 s45, 15, s43
	s_lshl_b32 s10, s3, 5
	s_and_b32 s1, s1, 0x3fffffc0
	s_and_b32 s2, s2, 0x700
	s_add_u32 s3, s18, s2
	s_addc_u32 s4, s19, 0
	s_lshl_b32 s5, s1, 1
	s_add_u32 s52, s3, s5
	s_addc_u32 s53, s4, 0
	s_add_u32 s54, s78, s2
	s_addc_u32 s55, s79, 0
	s_add_u32 s56, s80, s2
	s_addc_u32 s57, s81, 0
	s_cmpk_lt_u32 s0, 0x100
	s_cselect_b32 s4, s18, s6
	s_cselect_b32 s3, s19, s7
	s_add_u32 s2, s4, s2
	s_addc_u32 s3, s3, 0
	s_and_b32 s0, s0, 0x80
	s_add_u32 s58, s2, s0
	s_addc_u32 s59, s3, 0
	s_add_i32 s60, s43, 1
	s_lshl_b32 s61, s1, 1
	v_mov_b32_e32 v3, 0
	s_mov_b32 s62, 0x41000000
	v_mov_b32_e32 v231, 0x3727c5ac
	v_mov_b32_e32 v232, 0xff800000
	s_branch .LBB0_1058

.LBB0_1193:
	s_setprio 0
	v_readlane_b32 s0, v255, 3
	v_readlane_b32 s1, v255, 4
	s_cmp_gt_i32 s1, 16
	s_cselect_b64 s[2:3], -1, 0
	s_and_b64 s[0:1], s[8:9], s[2:3]
	s_andn2_b64 vcc, exec, s[0:1]
	s_cbranch_vccnz .LBB0_1247
	s_waitcnt vmcnt(0)
	s_waitcnt lgkmcnt(0)
	s_barrier
	s_mov_b64 s[4:5], exec
	v_readlane_b32 s0, v255, 9
	v_readlane_b32 s1, v255, 10
	s_and_b64 s[0:1], s[4:5], s[0:1]
	s_mov_b64 exec, s[0:1]
	s_cbranch_execz .LBB0_1246
	s_add_i32 s0, 0, 0x21160
	v_mov_b32_e32 v2, s0
	s_waitcnt vmcnt(0) expcnt(0) lgkmcnt(0)
	ds_read_b32 v4, v2
	s_add_i32 s0, 0, 0x21164
	v_mov_b32_e32 v2, s0
	ds_read_b32 v2, v2
	s_waitcnt lgkmcnt(1)
	v_cmp_ne_u32_e32 vcc, 0, v4
	s_cbranch_vccnz .LBB0_1210
	v_readlane_b32 s0, v255, 0
	v_readlane_b32 s1, v255, 1
	s_load_dwordx2 s[10:11], s[0:1], 0x4
	s_add_u32 s0, s70, 0x4200
	s_addc_u32 s1, s71, 0
	s_add_u32 s8, s70, 0x4400
	s_addc_u32 s9, s71, 0
	s_waitcnt lgkmcnt(0)
	s_mul_i32 s62, s10, s72
	s_add_u32 s10, s70, 0x4500
	s_mul_i32 s62, s62, s11
	s_addc_u32 s11, s71, 0
	s_add_u32 s20, s70, 0x4600
	s_addc_u32 s21, s71, 0
	s_add_u32 s22, s70, 0x4700
	s_addc_u32 s23, s71, 0
	s_add_u32 s24, s70, 0x4800
	s_addc_u32 s25, s71, 0
	s_add_u32 s26, s70, 0x4900
	s_addc_u32 s27, s71, 0
	s_add_u32 s34, s70, 0x4a00
	s_addc_u32 s35, s71, 0
	s_add_u32 s36, s70, 0x4b00
	s_addc_u32 s37, s71, 0
	s_add_u32 s38, s70, 0x4c00
	s_addc_u32 s39, s71, 0
	s_add_u32 s40, s70, 0x4d00
	s_addc_u32 s41, s71, 0
	s_add_u32 s42, s70, 0x4e00
	s_addc_u32 s43, s71, 0
	s_add_u32 s44, s70, 0x4f00
	s_addc_u32 s45, s71, 0
	s_add_u32 s50, s70, 0x5000
	s_addc_u32 s51, s71, 0
	s_add_u32 s52, s70, 0x5100
	s_addc_u32 s53, s71, 0
	s_add_u32 s54, s70, 0x5200
	s_addc_u32 s55, s71, 0
	s_add_u32 s56, s70, 0x5300
	s_addc_u32 s57, s71, 0
	s_mov_b32 s63, 1
	v_mov_b32_e32 v18, 0
	s_branch .LBB0_1198
